# NSA phase: query blocks dealt to workgroups from a 32-entry table balanced with measured slack (workgroups owning a cheap block qb<16 take larger other blocks, the rest smaller ones)
# speedup vs baseline: 1.0071x; 1.0047x over previous
.LBB0_1247:
	s_or_b64 exec, exec, s[10:11]
	v_lshlrev_b32_e32 v2, 10, v2
	s_add_i32 s62, 0, 0x1fc00
	v_lshlrev_b32_e32 v5, 2, v1
	v_add3_u32 v2, s62, v2, v5
	s_mov_b32 s27, 0
	ds_write_b32 v2, v4
	v_cmp_gt_u32_e32 vcc, 49, v1
	v_mov_b32_e32 v4, 0x1f0
	s_and_saveexec_b64 s[10:11], vcc
	v_cmp_lt_u32_e32 vcc, 2, v1
	s_nop 1
	v_cndmask_b32_e64 v4, 26, 27, vcc
	v_cmp_lt_u32_e32 vcc, 12, v1
	s_nop 1
	v_addc_co_u32_e32 v4, vcc, 0, v4, vcc
	v_cmp_lt_u32_e32 vcc, 22, v1
	s_nop 1
	v_cndmask_b32_e64 v5, 0, 1, vcc
	v_cmp_lt_u32_e32 vcc, 34, v1
	s_nop 1
	v_addc_co_u32_e32 v1, vcc, v4, v5, vcc
	v_lshlrev_b32_e32 v4, 4, v1
	s_or_b64 exec, exec, s[10:11]
	v_add_u32_e32 v4, v4, v3
	v_ashrrev_i32_e32 v5, 31, v4
	v_lshl_add_u64 v[4:5], v[4:5], 2, s[6:7]
	global_load_dword v1, v[4:5], off
	s_ashr_i32 s64, s14, 6
	s_mul_i32 s12, s64, 0x220
	s_mul_i32 s13, s64, 0x440
	s_and_b32 s63, s3, 31
	s_lshl_b32 s4, s3, 6
	s_mov_b32 s3, s27
	s_ashr_i32 s9, s8, 31
	s_add_i32 s86, s12, 0
	s_add_i32 s87, s13, 0
	s_xor_b32 s81, s63, 63
	s_or_b32 s82, s63, 64
	s_xor_b32 s83, s63, 0x7f
	s_lshl_b32 s84, s64, 3
	s_and_b32 s85, s4, 0xffffe000
	s_lshl_b64 s[38:39], s[2:3], 16
	s_lshl_b32 s3, s64, 5
	s_lshl_b64 s[4:5], s[8:9], 19
	s_lshl_b64 s[10:11], s[8:9], 20
	s_add_i32 s86, s86, 0x1b800
	s_add_i32 s87, s87, 0x1c900
	s_add_u32 s88, s10, 0x6e00000
	v_and_b32_e32 v3, 32, v0
	s_addc_u32 s89, s11, 0
	s_lshl_b64 s[40:41], s[8:9], 16
	s_lshl_b32 s8, s64, 12
	s_mov_b32 s28, 0x3fb8aa3b
	v_mov_b32_e32 v195, 0
	s_mov_b32 s65, 0xd000000
	s_movk_i32 s66, 0x90
	s_mov_b64 s[30:31], 0x8000000
	s_brev_b32 s67, 16
	s_mov_b32 s68, 0xff800000
	s_movk_i32 s69, 0x2000
	s_movk_i32 s71, 0x3000
	s_movk_i32 s76, 0x200
	s_mov_b64 s[34:35], 0x2000
	s_mov_b64 s[36:37], 0x4a00000
	s_mov_b32 s77, 0x4a00000
	s_movk_i32 s78, 0x104
	v_mov_b32_e32 v217, 0xff
	s_movk_i32 s79, 0xff
	s_mov_b32 s80, 0x48800000
	v_mov_b32_e32 v218, 1
	v_mov_b32_e32 v219, 0xff800000
	v_cmp_eq_u32_e64 s[6:7], 0, v3
	s_sub_i32 s90, s84, 31
	s_add_i32 s91, 0, 0x12800
	s_lshl_b64 s[42:43], s[4:5], 1
	s_add_i32 s92, 0, 0x1f000
	s_add_i32 s93, 0, 0x10c00
	s_add_i32 s94, s8, 0
	v_mov_b32_e32 v220, 0x7f
	v_mov_b32_e32 v221, 0x42c80001
	v_mov_b32_e32 v222, 0x3fb8aa3b
	s_mov_b32 s95, 0
	s_waitcnt vmcnt(0)
	v_mul_f32_e32 v1, 0x3fb8aa3b, v1
	ds_write_b32 v2, v1 offset:512
	s_waitcnt lgkmcnt(0)
	s_barrier
	s_mov_b32 s4, 0x7d716400
	v_writelane_b32 v251, s4, 0
	s_mov_b32 s4, 0x7b795601
	v_writelane_b32 v251, s4, 1
	s_mov_b32 s4, 0x7c765002
	v_writelane_b32 v251, s4, 2
	s_mov_b32 s4, 0x75735203
	v_writelane_b32 v251, s4, 3
	s_mov_b32 s4, 0x7f6a4804
	v_writelane_b32 v251, s4, 4
	s_mov_b32 s4, 0x7e654605
	v_writelane_b32 v251, s4, 5
	s_mov_b32 s4, 0x77575306
	v_writelane_b32 v251, s4, 6
	s_mov_b32 s4, 0x6c624b07
	v_writelane_b32 v251, s4, 7
	s_mov_b32 s4, 0x745f3d08
	v_writelane_b32 v251, s4, 8
	s_mov_b32 s4, 0x7a721c09
	v_writelane_b32 v251, s4, 9
	s_mov_b32 s4, 0x705b350a
	v_writelane_b32 v251, s4, 10
	s_mov_b32 s4, 0x674f420b
	v_writelane_b32 v251, s4, 11
	s_mov_b32 s4, 0x6860270c
	v_writelane_b32 v251, s4, 12
	s_mov_b32 s4, 0x5c55360d
	v_writelane_b32 v251, s4, 13
	s_mov_b32 s4, 0x635e1e0e
	v_writelane_b32 v251, s4, 14
	s_mov_b32 s4, 0x784d110f
	v_writelane_b32 v251, s4, 15
	s_mov_b32 s4, 0x4c442d23
	v_writelane_b32 v251, s4, 16
	s_mov_b32 s4, 0x4a413e17
	v_writelane_b32 v251, s4, 17
	s_mov_b32 s4, 0x61402b14
	v_writelane_b32 v251, s4, 18
	s_mov_b32 s4, 0x473f3129
	v_writelane_b32 v251, s4, 19
	s_mov_b32 s4, 0x433b3230
	v_writelane_b32 v251, s4, 20
	s_mov_b32 s4, 0x54332f2a
	v_writelane_b32 v251, s4, 21
	s_mov_b32 s4, 0x5d392624
	v_writelane_b32 v251, s4, 22
	s_mov_b32 s4, 0x6e342c12
	v_writelane_b32 v251, s4, 23
	s_mov_b32 s4, 0x6d3c1d1a
	v_writelane_b32 v251, s4, 24
	s_mov_b32 s4, 0x5a452120
	v_writelane_b32 v251, s4, 25
	s_mov_b32 s4, 0x66511910
	v_writelane_b32 v251, s4, 26
	s_mov_b32 s4, 0x59372e22
	v_writelane_b32 v251, s4, 27
	s_mov_b32 s4, 0x6f3a1f18
	v_writelane_b32 v251, s4, 28
	s_mov_b32 s4, 0x5849251b
	v_writelane_b32 v251, s4, 29
	s_mov_b32 s4, 0x694e1613
	v_writelane_b32 v251, s4, 30
	s_mov_b32 s4, 0x6b382815
	v_writelane_b32 v251, s4, 31
	s_branch .LBB0_1252

.LBB0_1252:
	v_readlane_b32 s4, v251, s63
	s_and_b32 s101, s4, 0xff
	s_bfe_u32 s81, s4, 0x80008
	s_bfe_u32 s82, s4, 0x80010
	s_lshr_b32 s83, s4, 24
	v_mov_b32_e32 v210, v197
	s_mov_b64 s[8:9], s[0:1]
	s_load_dwordx2 s[4:5], s[8:9], 0x10
	v_and_b32_e32 v227, 3, v210
	v_or_b32_e32 v4, s29, v227
	v_lshlrev_b32_e32 v2, 2, v4
	s_cmp_lt_i32 s95, 1
	s_waitcnt lgkmcnt(0)
	global_load_dword v5, v2, s[4:5] offset:1984
	s_mov_b32 s44, s101
	s_cbranch_scc1 .LBB0_1257
	s_cmp_lg_u32 s95, 1
	s_mov_b64 s[8:9], -1
	s_cbranch_scc0 .LBB0_1255
	s_cmp_eq_u32 s95, 2
	s_cselect_b32 s44, s82, s83
	s_mov_b64 s[8:9], 0

	.amdhsa_kernel _Z10fwd_kernel4Args
		.amdhsa_group_segment_fixed_size 0
		.amdhsa_private_segment_fixed_size 0
		.amdhsa_kernarg_size 440
		.amdhsa_user_sgpr_count 2
		.amdhsa_user_sgpr_dispatch_ptr 0
		.amdhsa_user_sgpr_queue_ptr 0
		.amdhsa_user_sgpr_kernarg_segment_ptr 1
		.amdhsa_user_sgpr_dispatch_id 0
		.amdhsa_user_sgpr_kernarg_preload_length 0
		.amdhsa_user_sgpr_kernarg_preload_offset 0
		.amdhsa_user_sgpr_private_segment_size 0
		.amdhsa_uses_dynamic_stack 0
		.amdhsa_enable_private_segment 0
		.amdhsa_system_sgpr_workgroup_id_x 1
		.amdhsa_system_sgpr_workgroup_id_y 0
		.amdhsa_system_sgpr_workgroup_id_z 0
		.amdhsa_system_sgpr_workgroup_info 0
		.amdhsa_system_vgpr_workitem_id 0
		.amdhsa_next_free_vgpr 252
		.amdhsa_next_free_sgpr 102
		.amdhsa_accum_offset 252
		.amdhsa_reserve_vcc 1
		.amdhsa_float_round_mode_32 0
		.amdhsa_float_round_mode_16_64 0
		.amdhsa_float_denorm_mode_32 3
		.amdhsa_float_denorm_mode_16_64 3
		.amdhsa_dx10_clamp 1
		.amdhsa_ieee_mode 1
		.amdhsa_fp16_overflow 0
		.amdhsa_tg_split 0
		.amdhsa_exception_fp_ieee_invalid_op 0
		.amdhsa_exception_fp_denorm_src 0
		.amdhsa_exception_fp_ieee_div_zero 0
		.amdhsa_exception_fp_ieee_overflow 0
		.amdhsa_exception_fp_ieee_underflow 0
		.amdhsa_exception_fp_ieee_inexact 0
		.amdhsa_exception_int_div_zero 0
	.end_amdhsa_kernel

amdhsa.kernels:
  - .agpr_count:     0
    .args:
      - .offset:         0
        .size:           184
        .value_kind:     by_value
      - .offset:         184
        .size:           4
        .value_kind:     hidden_block_count_x
      - .offset:         188
        .size:           4
        .value_kind:     hidden_block_count_y
      - .offset:         192
        .size:           4
        .value_kind:     hidden_block_count_z
      - .offset:         196
        .size:           2
        .value_kind:     hidden_group_size_x
      - .offset:         198
        .size:           2
        .value_kind:     hidden_group_size_y
      - .offset:         200
        .size:           2
        .value_kind:     hidden_group_size_z
      - .offset:         202
        .size:           2
        .value_kind:     hidden_remainder_x
      - .offset:         204
        .size:           2
        .value_kind:     hidden_remainder_y
      - .offset:         206
        .size:           2
        .value_kind:     hidden_remainder_z
      - .offset:         224
        .size:           8
        .value_kind:     hidden_global_offset_x
      - .offset:         232
        .size:           8
        .value_kind:     hidden_global_offset_y
      - .offset:         240
        .size:           8
        .value_kind:     hidden_global_offset_z
      - .offset:         248
        .size:           2
        .value_kind:     hidden_grid_dims
      - .offset:         304
        .size:           4
        .value_kind:     hidden_dynamic_lds_size
    .group_segment_fixed_size: 0
    .kernarg_segment_align: 8
    .kernarg_segment_size: 440
    .language:       OpenCL C
    .language_version:
      - 2
      - 0
    .max_flat_workgroup_size: 512
    .name:           _Z10fwd_kernel4Args
    .private_segment_fixed_size: 0
    .sgpr_count:     108
    .sgpr_spill_count: 4
    .symbol:         _Z10fwd_kernel4Args.kd
    .uniform_work_group_size: 1
    .uses_dynamic_stack: false
    .vgpr_count:     252
    .vgpr_spill_count: 0
    .wavefront_size: 64
